# LN1+router row loop hand-rewritten: ds_bpermute shuffles -> DPP/permlane swaps, router weight LDS reads pipelined 3 groups deep, packed FMAs (same arithmetic order)
# speedup vs baseline: 1.0466x; 1.0106x over previous
; #define LAS __attribute__((address_space(3)))
; DI unsigned pk2(float lo, float hi) { f32x2 v = {lo, hi}; bf16x2v b = __builtin_convertvector(v, bf16x2v); return __builtin_bit_cast(unsigned, b); }
; DI float bflo(unsigned u) { return __uint_as_float(u << 16); }
; DI float bfhi(unsigned u) { return __uint_as_float(u & 0xffff0000u); }
; DI float frsq(float x) { return __builtin_amdgcn_rsqf(x); }
; DI void phase_ln1(KArgs args, LAS unsigned char* L, const Ctx& c) {
;     ...
;     for (int rl = c.bid * 8 + c.wave; rl < c.stok; rl += c.G * 8) { const size_t tok = (size_t)c.sbase + rl;
;         const bf16_t* hr = (const bf16_t*)c.out + tok * D; f32x4 v[4]; float s = 0.f;
; #pragma unroll
;         for (int j = 0; j < 4; ++j) { v[j][0] = bflo(nv[j].x); v[j][1] = bfhi(nv[j].x); v[j][2] = bflo(nv[j].y); v[j][3] = bfhi(nv[j].y); s += (v[j][0] + v[j][1]) + (v[j][2] + v[j][3]); }
;         if (rl + c.G * 8 < c.stok) { const bf16_t* hp = hr + (size_t)c.G * 8 * D;
; #pragma unroll
;             for (int j = 0; j < 4; ++j) nv[j] = *(const u32x2*)(hp + 4 * lane + 256 * j); }
;         const float mean = wave_sum(s) * (1.0f / D); float s2 = 0.f;
; #pragma unroll
;         for (int j = 0; j < 4; ++j) { v[j] = v[j] - mean; s2 += (v[j][0] * v[j][0] + v[j][1] * v[j][1]) + (v[j][2] * v[j][2] + v[j][3] * v[j][3]); }
;         const float rstd = frsq(wave_sum(s2) * (1.0f / D) + LN_EPS);
;         float lg[16];
; #pragma unroll
;         for (int e = 0; e < 16; ++e) lg[e] = 0.f;
; #pragma unroll
;         for (int j = 0; j < 4; ++j) { v[j] = v[j] * rstd * gv[j] + bv[j];
;             if (!c.dry) { u32x2 w; w.x = pk2(v[j][0], v[j][1]); w.y = pk2(v[j][2], v[j][3]); *(u32x2*)(XB + tok * D + 4 * lane + 256 * j) = w; }
; #pragma unroll
;             for (int q = 0; q < 4; ++q) { const LAS float* wp = WR + ((j * 4 + q) * 64 + lane) * 20; const float xv = v[j][q];
; #pragma unroll
;                 for (int e4 = 0; e4 < 4; ++e4) { const f32x4 w4 = *(const LAS f32x4*)(wp + 4 * e4); lg[4 * e4] += xv * w4[0]; lg[4 * e4 + 1] += xv * w4[1]; lg[4 * e4 + 2] += xv * w4[2]; lg[4 * e4 + 3] += xv * w4[3]; } }
;             asm volatile("" ::: "memory"); }
.LBB0_1223:
	ds_read_b128 v[114:117], v1 offset:0
	ds_read_b128 v[118:121], v1 offset:16
	ds_read_b128 v[122:125], v1 offset:32
	ds_read_b128 v[126:129], v1 offset:48
	ds_read_b128 v[130:133], v1 offset:5120
	ds_read_b128 v[134:137], v1 offset:5136
	ds_read_b128 v[138:141], v1 offset:5152
	ds_read_b128 v[142:145], v1 offset:5168
	s_waitcnt vmcnt(7)
	v_lshlrev_b32_e32 v82, 16, v54
	v_and_b32_e32 v83, 0xffff0000, v54
	v_lshlrev_b32_e32 v84, 16, v55
	v_and_b32_e32 v85, 0xffff0000, v55
	v_add_f32_e32 v54, v82, v83
	v_add_f32_e32 v55, v84, v85
	s_waitcnt vmcnt(6)
	v_lshlrev_b32_e32 v60, 16, v52
	v_and_b32_e32 v61, 0xffff0000, v52
	v_lshlrev_b32_e32 v62, 16, v53
	v_and_b32_e32 v63, 0xffff0000, v53
	v_add_f32_e32 v54, v54, v55
	v_add_f32_e32 v52, v60, v61
	v_add_f32_e32 v53, v62, v63
	s_waitcnt vmcnt(5)
	v_lshlrev_b32_e32 v56, 16, v50
	v_and_b32_e32 v57, 0xffff0000, v50
	v_lshlrev_b32_e32 v58, 16, v51
	v_and_b32_e32 v59, 0xffff0000, v51
	v_add_f32_e32 v54, 0, v54
	v_add_f32_e32 v52, v52, v53
	v_add_f32_e32 v50, v56, v57
	v_add_f32_e32 v51, v58, v59
	v_add_f32_e32 v52, v52, v54
	v_add_f32_e32 v50, v50, v51
	v_add_f32_e32 v54, v50, v52
	s_waitcnt vmcnt(4)
	v_lshlrev_b32_e32 v52, 16, v48
	v_and_b32_e32 v53, 0xffff0000, v48
	v_lshlrev_b32_e32 v50, 16, v49
	v_and_b32_e32 v51, 0xffff0000, v49
	v_add_f32_e32 v48, v52, v53
	v_add_f32_e32 v49, v50, v51
	v_add_f32_e32 v48, v48, v49
	v_add_f32_e32 v48, v48, v54
	s_nop 1
	v_add_f32_dpp v48, v48, v48 quad_perm:[1,0,3,2] row_mask:0xf bank_mask:0xf
	s_nop 1
	v_add_f32_dpp v48, v48, v48 quad_perm:[2,3,0,1] row_mask:0xf bank_mask:0xf
	s_nop 1
	v_add_f32_dpp v48, v48, v48 row_half_mirror row_mask:0xf bank_mask:0xf
	s_nop 1
	v_add_f32_dpp v48, v48, v48 row_mirror row_mask:0xf bank_mask:0xf
	s_nop 1
	v_add_f32_dpp v48, v48, v48 row_bcast:15 row_mask:0xa bank_mask:0xf
	s_nop 1
	v_add_f32_dpp v48, v48, v48 row_bcast:31 row_mask:0xc bank_mask:0xf
	s_nop 1
	v_readlane_b32 s28, v48, 63
	s_mov_b32 s1, 0x3fb8aa3b
	s_nop 0
	v_mov_b32_e32 v90, s28
	v_fmac_f32_e32 v83, 0xba800000, v90
	v_fmac_f32_e32 v82, 0xba800000, v90
	v_fmac_f32_e32 v85, 0xba800000, v90
	v_fmac_f32_e32 v84, 0xba800000, v90
	v_pk_mul_f32 v[48:49], v[84:85], v[84:85]
	v_pk_mul_f32 v[54:55], v[82:83], v[82:83]
	v_fmac_f32_e32 v61, 0xba800000, v90
	v_pk_mov_b32 v[86:87], v[54:55], v[48:49] op_sel:[1,0]
	v_mov_b32_e32 v55, v49
	v_pk_add_f32 v[48:49], v[86:87], v[54:55]
	v_fmac_f32_e32 v60, 0xba800000, v90
	v_fmac_f32_e32 v63, 0xba800000, v90
	v_fmac_f32_e32 v62, 0xba800000, v90
	v_pk_add_f32 v[48:49], v[48:49], v[48:49] op_sel_hi:[0,1]
	v_pk_mul_f32 v[54:55], v[62:63], v[62:63]
	v_pk_mul_f32 v[86:87], v[60:61], v[60:61]
	v_fmac_f32_e32 v56, 0xba800000, v90
	v_pk_mov_b32 v[88:89], v[86:87], v[54:55] op_sel:[1,0]
	v_mov_b32_e32 v87, v55
	v_fmac_f32_e32 v57, 0xba800000, v90
	v_fmac_f32_e32 v58, 0xba800000, v90
	v_mul_f32_e32 v48, v56, v56
	v_pk_add_f32 v[54:55], v[88:89], v[86:87]
	v_fmac_f32_e32 v59, 0xba800000, v90
	v_pk_fma_f32 v[86:87], v[56:57], v[56:57], v[48:49] op_sel_hi:[1,1,0]
	v_mul_f32_e32 v48, v58, v58
	v_pk_add_f32 v[54:55], v[54:55], v[54:55] op_sel_hi:[0,1]
	v_pk_fma_f32 v[88:89], v[58:59], v[58:59], v[48:49] op_sel_hi:[1,1,0]
	v_fmac_f32_e32 v51, 0xba800000, v90
	v_fmac_f32_e32 v50, 0xba800000, v90
	v_fmac_f32_e32 v53, 0xba800000, v90
	v_fmac_f32_e32 v52, 0xba800000, v90
	v_mul_f32_e32 v86, v52, v52
	v_mul_f32_e32 v88, v53, v53
	v_mul_f32_e32 v48, v50, v50
	v_mul_f32_e32 v54, v51, v51
	v_pk_add_f32 v[86:87], v[86:87], v[88:89]
	v_pk_add_f32 v[48:49], v[48:49], v[54:55]
	s_nop 0
	v_pk_add_f32 v[48:49], v[86:87], v[48:49]
	s_nop 0
	v_add_f32_e32 v48, v48, v49
	s_nop 1
	v_add_f32_dpp v48, v48, v48 quad_perm:[1,0,3,2] row_mask:0xf bank_mask:0xf
	s_nop 1
	v_add_f32_dpp v48, v48, v48 quad_perm:[2,3,0,1] row_mask:0xf bank_mask:0xf
	s_nop 1
	v_add_f32_dpp v48, v48, v48 row_half_mirror row_mask:0xf bank_mask:0xf
	s_nop 1
	v_add_f32_dpp v48, v48, v48 row_mirror row_mask:0xf bank_mask:0xf
	s_nop 1
	v_add_f32_dpp v48, v48, v48 row_bcast:15 row_mask:0xa bank_mask:0xf
	s_nop 1
	v_add_f32_dpp v48, v48, v48 row_bcast:31 row_mask:0xc bank_mask:0xf
	s_nop 1
	v_readlane_b32 s28, v48, 63
	s_nop 1
	v_mov_b32_e32 v48, s28
	v_fmamk_f32 v48, v48, 0x3a800000, v214
	v_rsq_f32_e32 v54, v48
	v_lshl_add_u64 v[48:49], s[18:19], 0, v[2:3]
	v_pk_mul_f32 v[82:83], v[82:83], v[54:55] op_sel_hi:[1,0]
	v_pk_mul_f32 v[84:85], v[84:85], v[54:55] op_sel_hi:[1,0]
	v_pk_fma_f32 v[110:111], v[32:33], v[82:83], v[24:25]
	v_pk_fma_f32 v[108:109], v[34:35], v[84:85], v[26:27]
	v_cvt_pk_bf16_f32 v86, v110, v111
	v_cvt_pk_bf16_f32 v87, v108, v109
	global_store_dwordx2 v[48:49], v[86:87], off offset:-1024
	s_waitcnt lgkmcnt(4)
	ds_read_b128 v[146:149], v1 offset:10240
	ds_read_b128 v[150:153], v1 offset:10256
	ds_read_b128 v[154:157], v1 offset:10272
	ds_read_b128 v[158:161], v1 offset:10288
	v_pk_mul_f32 v[162:163], v[114:115], v[110:111] op_sel_hi:[1,0]
	v_pk_mul_f32 v[164:165], v[116:117], v[110:111] op_sel_hi:[1,0]
	v_pk_mul_f32 v[166:167], v[118:119], v[110:111] op_sel_hi:[1,0]
	v_pk_mul_f32 v[168:169], v[120:121], v[110:111] op_sel_hi:[1,0]
	v_pk_mul_f32 v[170:171], v[122:123], v[110:111] op_sel_hi:[1,0]
	v_pk_mul_f32 v[172:173], v[124:125], v[110:111] op_sel_hi:[1,0]
	v_pk_mul_f32 v[174:175], v[126:127], v[110:111] op_sel_hi:[1,0]
	v_pk_mul_f32 v[176:177], v[128:129], v[110:111] op_sel_hi:[1,0]
	s_waitcnt lgkmcnt(4)
; #define LAS __attribute__((address_space(3)))
; DI unsigned pk2(float lo, float hi) { f32x2 v = {lo, hi}; bf16x2v b = __builtin_convertvector(v, bf16x2v); return __builtin_bit_cast(unsigned, b); }
; DI void phase_ln1(KArgs args, LAS unsigned char* L, const Ctx& c) {
;     ...
;         for (int j = 0; j < 4; ++j) { v[j] = v[j] * rstd * gv[j] + bv[j];
;             if (!c.dry) { u32x2 w; w.x = pk2(v[j][0], v[j][1]); w.y = pk2(v[j][2], v[j][3]); *(u32x2*)(XB + tok * D + 4 * lane + 256 * j) = w; }
; #pragma unroll
;             for (int q = 0; q < 4; ++q) { const LAS float* wp = WR + ((j * 4 + q) * 64 + lane) * 20; const float xv = v[j][q];
; #pragma unroll
;                 for (int e4 = 0; e4 < 4; ++e4) { const f32x4 w4 = *(const LAS f32x4*)(wp + 4 * e4); lg[4 * e4] += xv * w4[0]; lg[4 * e4 + 1] += xv * w4[1]; lg[4 * e4 + 2] += xv * w4[2]; lg[4 * e4 + 3] += xv * w4[3]; } }
	ds_read_b128 v[114:117], v1 offset:15360
	ds_read_b128 v[118:121], v1 offset:15376
	ds_read_b128 v[122:125], v1 offset:15392
	ds_read_b128 v[126:129], v1 offset:15408
	v_pk_fma_f32 v[162:163], v[130:131], v[110:111], v[162:163] op_sel:[0,1,0]
	v_pk_fma_f32 v[164:165], v[132:133], v[110:111], v[164:165] op_sel:[0,1,0]
	v_pk_fma_f32 v[166:167], v[134:135], v[110:111], v[166:167] op_sel:[0,1,0]
	v_pk_fma_f32 v[168:169], v[136:137], v[110:111], v[168:169] op_sel:[0,1,0]
	v_pk_fma_f32 v[170:171], v[138:139], v[110:111], v[170:171] op_sel:[0,1,0]
	v_pk_fma_f32 v[172:173], v[140:141], v[110:111], v[172:173] op_sel:[0,1,0]
	v_pk_fma_f32 v[174:175], v[142:143], v[110:111], v[174:175] op_sel:[0,1,0]
	v_pk_fma_f32 v[176:177], v[144:145], v[110:111], v[176:177] op_sel:[0,1,0]
	s_waitcnt lgkmcnt(4)
	ds_read_b128 v[130:133], v1 offset:20480
	ds_read_b128 v[134:137], v1 offset:20496
	ds_read_b128 v[138:141], v1 offset:20512
	ds_read_b128 v[142:145], v1 offset:20528
	v_pk_fma_f32 v[162:163], v[146:147], v[108:109], v[162:163] op_sel_hi:[1,0,1]
	v_pk_fma_f32 v[164:165], v[148:149], v[108:109], v[164:165] op_sel_hi:[1,0,1]
	v_pk_fma_f32 v[166:167], v[150:151], v[108:109], v[166:167] op_sel_hi:[1,0,1]
	v_pk_fma_f32 v[168:169], v[152:153], v[108:109], v[168:169] op_sel_hi:[1,0,1]
	v_pk_fma_f32 v[170:171], v[154:155], v[108:109], v[170:171] op_sel_hi:[1,0,1]
	v_pk_fma_f32 v[172:173], v[156:157], v[108:109], v[172:173] op_sel_hi:[1,0,1]
	v_pk_fma_f32 v[174:175], v[158:159], v[108:109], v[174:175] op_sel_hi:[1,0,1]
	v_pk_fma_f32 v[176:177], v[160:161], v[108:109], v[176:177] op_sel_hi:[1,0,1]
	s_waitcnt lgkmcnt(4)
	ds_read_b128 v[146:149], v1 offset:25600
	ds_read_b128 v[150:153], v1 offset:25616
	ds_read_b128 v[154:157], v1 offset:25632
	ds_read_b128 v[158:161], v1 offset:25648
	v_pk_fma_f32 v[162:163], v[114:115], v[108:109], v[162:163] op_sel:[0,1,0]
	v_pk_fma_f32 v[164:165], v[116:117], v[108:109], v[164:165] op_sel:[0,1,0]
	v_pk_fma_f32 v[166:167], v[118:119], v[108:109], v[166:167] op_sel:[0,1,0]
	v_pk_fma_f32 v[168:169], v[120:121], v[108:109], v[168:169] op_sel:[0,1,0]
	v_pk_fma_f32 v[170:171], v[122:123], v[108:109], v[170:171] op_sel:[0,1,0]
	v_pk_fma_f32 v[172:173], v[124:125], v[108:109], v[172:173] op_sel:[0,1,0]
	v_pk_fma_f32 v[174:175], v[126:127], v[108:109], v[174:175] op_sel:[0,1,0]
	v_pk_fma_f32 v[176:177], v[128:129], v[108:109], v[176:177] op_sel:[0,1,0]
	v_pk_mul_f32 v[60:61], v[60:61], v[54:55] op_sel_hi:[1,0]
	v_pk_mul_f32 v[62:63], v[62:63], v[54:55] op_sel_hi:[1,0]
	v_pk_fma_f32 v[112:113], v[28:29], v[60:61], v[20:21]
	v_pk_fma_f32 v[110:111], v[30:31], v[62:63], v[22:23]
	v_cvt_pk_bf16_f32 v88, v112, v113
	v_cvt_pk_bf16_f32 v89, v110, v111
	global_store_dwordx2 v[48:49], v[88:89], off offset:-512
	s_waitcnt lgkmcnt(4)
	ds_read_b128 v[114:117], v1 offset:30720
	ds_read_b128 v[118:121], v1 offset:30736
	ds_read_b128 v[122:125], v1 offset:30752
	ds_read_b128 v[126:129], v1 offset:30768
	v_pk_fma_f32 v[162:163], v[130:131], v[112:113], v[162:163] op_sel_hi:[1,0,1]
	v_pk_fma_f32 v[164:165], v[132:133], v[112:113], v[164:165] op_sel_hi:[1,0,1]
	v_pk_fma_f32 v[166:167], v[134:135], v[112:113], v[166:167] op_sel_hi:[1,0,1]
	v_pk_fma_f32 v[168:169], v[136:137], v[112:113], v[168:169] op_sel_hi:[1,0,1]
	v_pk_fma_f32 v[170:171], v[138:139], v[112:113], v[170:171] op_sel_hi:[1,0,1]
	v_pk_fma_f32 v[172:173], v[140:141], v[112:113], v[172:173] op_sel_hi:[1,0,1]
	v_pk_fma_f32 v[174:175], v[142:143], v[112:113], v[174:175] op_sel_hi:[1,0,1]
	v_pk_fma_f32 v[176:177], v[144:145], v[112:113], v[176:177] op_sel_hi:[1,0,1]
	s_waitcnt lgkmcnt(4)
	ds_read_b128 v[130:133], v1 offset:35840
	ds_read_b128 v[134:137], v1 offset:35856
	ds_read_b128 v[138:141], v1 offset:35872
	ds_read_b128 v[142:145], v1 offset:35888
	v_pk_fma_f32 v[162:163], v[146:147], v[112:113], v[162:163] op_sel:[0,1,0]
	v_pk_fma_f32 v[164:165], v[148:149], v[112:113], v[164:165] op_sel:[0,1,0]
	v_pk_fma_f32 v[166:167], v[150:151], v[112:113], v[166:167] op_sel:[0,1,0]
	v_pk_fma_f32 v[168:169], v[152:153], v[112:113], v[168:169] op_sel:[0,1,0]
	v_pk_fma_f32 v[170:171], v[154:155], v[112:113], v[170:171] op_sel:[0,1,0]
	v_pk_fma_f32 v[172:173], v[156:157], v[112:113], v[172:173] op_sel:[0,1,0]
	v_pk_fma_f32 v[174:175], v[158:159], v[112:113], v[174:175] op_sel:[0,1,0]
	v_pk_fma_f32 v[176:177], v[160:161], v[112:113], v[176:177] op_sel:[0,1,0]
	s_waitcnt lgkmcnt(4)
	ds_read_b128 v[146:149], v1 offset:40960
	ds_read_b128 v[150:153], v1 offset:40976
	ds_read_b128 v[154:157], v1 offset:40992
	ds_read_b128 v[158:161], v1 offset:41008
	v_pk_fma_f32 v[162:163], v[114:115], v[110:111], v[162:163] op_sel_hi:[1,0,1]
	v_pk_fma_f32 v[164:165], v[116:117], v[110:111], v[164:165] op_sel_hi:[1,0,1]
	v_pk_fma_f32 v[166:167], v[118:119], v[110:111], v[166:167] op_sel_hi:[1,0,1]
	v_pk_fma_f32 v[168:169], v[120:121], v[110:111], v[168:169] op_sel_hi:[1,0,1]
	v_pk_fma_f32 v[170:171], v[122:123], v[110:111], v[170:171] op_sel_hi:[1,0,1]
	v_pk_fma_f32 v[172:173], v[124:125], v[110:111], v[172:173] op_sel_hi:[1,0,1]
	v_pk_fma_f32 v[174:175], v[126:127], v[110:111], v[174:175] op_sel_hi:[1,0,1]
	v_pk_fma_f32 v[176:177], v[128:129], v[110:111], v[176:177] op_sel_hi:[1,0,1]
	s_waitcnt lgkmcnt(4)
; #define LAS __attribute__((address_space(3)))
; DI unsigned pk2(float lo, float hi) { f32x2 v = {lo, hi}; bf16x2v b = __builtin_convertvector(v, bf16x2v); return __builtin_bit_cast(unsigned, b); }
; DI void phase_ln1(KArgs args, LAS unsigned char* L, const Ctx& c) {
;     ...
;         for (int j = 0; j < 4; ++j) { v[j] = v[j] * rstd * gv[j] + bv[j];
;             if (!c.dry) { u32x2 w; w.x = pk2(v[j][0], v[j][1]); w.y = pk2(v[j][2], v[j][3]); *(u32x2*)(XB + tok * D + 4 * lane + 256 * j) = w; }
; #pragma unroll
;             for (int q = 0; q < 4; ++q) { const LAS float* wp = WR + ((j * 4 + q) * 64 + lane) * 20; const float xv = v[j][q];
; #pragma unroll
;                 for (int e4 = 0; e4 < 4; ++e4) { const f32x4 w4 = *(const LAS f32x4*)(wp + 4 * e4); lg[4 * e4] += xv * w4[0]; lg[4 * e4 + 1] += xv * w4[1]; lg[4 * e4 + 2] += xv * w4[2]; lg[4 * e4 + 3] += xv * w4[3]; } }
	ds_read_b128 v[114:117], v1 offset:46080
	ds_read_b128 v[118:121], v1 offset:46096
	ds_read_b128 v[122:125], v1 offset:46112
	ds_read_b128 v[126:129], v1 offset:46128
	v_pk_fma_f32 v[162:163], v[130:131], v[110:111], v[162:163] op_sel:[0,1,0]
	v_pk_fma_f32 v[164:165], v[132:133], v[110:111], v[164:165] op_sel:[0,1,0]
	v_pk_fma_f32 v[166:167], v[134:135], v[110:111], v[166:167] op_sel:[0,1,0]
	v_pk_fma_f32 v[168:169], v[136:137], v[110:111], v[168:169] op_sel:[0,1,0]
	v_pk_fma_f32 v[170:171], v[138:139], v[110:111], v[170:171] op_sel:[0,1,0]
	v_pk_fma_f32 v[172:173], v[140:141], v[110:111], v[172:173] op_sel:[0,1,0]
	v_pk_fma_f32 v[174:175], v[142:143], v[110:111], v[174:175] op_sel:[0,1,0]
	v_pk_fma_f32 v[176:177], v[144:145], v[110:111], v[176:177] op_sel:[0,1,0]
	v_pk_mul_f32 v[56:57], v[56:57], v[54:55] op_sel_hi:[1,0]
	v_pk_mul_f32 v[58:59], v[58:59], v[54:55] op_sel_hi:[1,0]
	v_pk_fma_f32 v[108:109], v[16:17], v[56:57], v[8:9]
	v_pk_fma_f32 v[106:107], v[18:19], v[58:59], v[10:11]
	v_cvt_pk_bf16_f32 v98, v108, v109
	v_cvt_pk_bf16_f32 v99, v106, v107
	global_store_dwordx2 v[48:49], v[98:99], off
	s_waitcnt lgkmcnt(4)
	ds_read_b128 v[130:133], v1 offset:51200
	ds_read_b128 v[134:137], v1 offset:51216
	ds_read_b128 v[138:141], v1 offset:51232
	ds_read_b128 v[142:145], v1 offset:51248
	v_pk_fma_f32 v[162:163], v[146:147], v[108:109], v[162:163] op_sel_hi:[1,0,1]
	v_pk_fma_f32 v[164:165], v[148:149], v[108:109], v[164:165] op_sel_hi:[1,0,1]
	v_pk_fma_f32 v[166:167], v[150:151], v[108:109], v[166:167] op_sel_hi:[1,0,1]
	v_pk_fma_f32 v[168:169], v[152:153], v[108:109], v[168:169] op_sel_hi:[1,0,1]
	v_pk_fma_f32 v[170:171], v[154:155], v[108:109], v[170:171] op_sel_hi:[1,0,1]
	v_pk_fma_f32 v[172:173], v[156:157], v[108:109], v[172:173] op_sel_hi:[1,0,1]
	v_pk_fma_f32 v[174:175], v[158:159], v[108:109], v[174:175] op_sel_hi:[1,0,1]
	v_pk_fma_f32 v[176:177], v[160:161], v[108:109], v[176:177] op_sel_hi:[1,0,1]
	s_waitcnt lgkmcnt(4)
	ds_read_b128 v[146:149], v1 offset:56320
	ds_read_b128 v[150:153], v1 offset:56336
	ds_read_b128 v[154:157], v1 offset:56352
	ds_read_b128 v[158:161], v1 offset:56368
	v_pk_fma_f32 v[162:163], v[114:115], v[108:109], v[162:163] op_sel:[0,1,0]
	v_pk_fma_f32 v[164:165], v[116:117], v[108:109], v[164:165] op_sel:[0,1,0]
	v_pk_fma_f32 v[166:167], v[118:119], v[108:109], v[166:167] op_sel:[0,1,0]
	v_pk_fma_f32 v[168:169], v[120:121], v[108:109], v[168:169] op_sel:[0,1,0]
	v_pk_fma_f32 v[170:171], v[122:123], v[108:109], v[170:171] op_sel:[0,1,0]
	v_pk_fma_f32 v[172:173], v[124:125], v[108:109], v[172:173] op_sel:[0,1,0]
	v_pk_fma_f32 v[174:175], v[126:127], v[108:109], v[174:175] op_sel:[0,1,0]
	v_pk_fma_f32 v[176:177], v[128:129], v[108:109], v[176:177] op_sel:[0,1,0]
	s_waitcnt lgkmcnt(4)
	ds_read_b128 v[114:117], v1 offset:61440
	ds_read_b128 v[118:121], v1 offset:61456
	ds_read_b128 v[122:125], v1 offset:61472
	ds_read_b128 v[126:129], v1 offset:61488
	v_pk_fma_f32 v[162:163], v[130:131], v[106:107], v[162:163] op_sel_hi:[1,0,1]
	v_pk_fma_f32 v[164:165], v[132:133], v[106:107], v[164:165] op_sel_hi:[1,0,1]
	v_pk_fma_f32 v[166:167], v[134:135], v[106:107], v[166:167] op_sel_hi:[1,0,1]
	v_pk_fma_f32 v[168:169], v[136:137], v[106:107], v[168:169] op_sel_hi:[1,0,1]
	v_pk_fma_f32 v[170:171], v[138:139], v[106:107], v[170:171] op_sel_hi:[1,0,1]
	v_pk_fma_f32 v[172:173], v[140:141], v[106:107], v[172:173] op_sel_hi:[1,0,1]
	v_pk_fma_f32 v[174:175], v[142:143], v[106:107], v[174:175] op_sel_hi:[1,0,1]
	v_pk_fma_f32 v[176:177], v[144:145], v[106:107], v[176:177] op_sel_hi:[1,0,1]
	s_waitcnt lgkmcnt(4)
	ds_read_b128 v[130:133], v64
	ds_read_b128 v[134:137], v65
	ds_read_b128 v[138:141], v66
	ds_read_b128 v[142:145], v67
	v_pk_fma_f32 v[162:163], v[146:147], v[106:107], v[162:163] op_sel:[0,1,0]
	v_pk_fma_f32 v[164:165], v[148:149], v[106:107], v[164:165] op_sel:[0,1,0]
	v_pk_fma_f32 v[166:167], v[150:151], v[106:107], v[166:167] op_sel:[0,1,0]
	v_pk_fma_f32 v[168:169], v[152:153], v[106:107], v[168:169] op_sel:[0,1,0]
	v_pk_fma_f32 v[170:171], v[154:155], v[106:107], v[170:171] op_sel:[0,1,0]
	v_pk_fma_f32 v[172:173], v[156:157], v[106:107], v[172:173] op_sel:[0,1,0]
	v_pk_fma_f32 v[174:175], v[158:159], v[106:107], v[174:175] op_sel:[0,1,0]
	v_pk_fma_f32 v[176:177], v[160:161], v[106:107], v[176:177] op_sel:[0,1,0]
	v_pk_mul_f32 v[52:53], v[52:53], v[54:55] op_sel_hi:[1,0]
	v_pk_mul_f32 v[50:51], v[50:51], v[54:55] op_sel_hi:[1,0]
	v_pk_fma_f32 v[52:53], v[12:13], v[52:53], v[4:5]
	v_pk_fma_f32 v[50:51], v[14:15], v[50:51], v[6:7]
	v_cvt_pk_bf16_f32 v100, v52, v53
	v_cvt_pk_bf16_f32 v101, v50, v51
	global_store_dwordx2 v[48:49], v[100:101], off offset:512
	s_waitcnt lgkmcnt(4)
	ds_read_b128 v[146:149], v68
	ds_read_b128 v[150:153], v69
	ds_read_b128 v[154:157], v70
	ds_read_b128 v[158:161], v71
	v_pk_fma_f32 v[162:163], v[114:115], v[52:53], v[162:163] op_sel_hi:[1,0,1]
	v_pk_fma_f32 v[164:165], v[116:117], v[52:53], v[164:165] op_sel_hi:[1,0,1]
	v_pk_fma_f32 v[166:167], v[118:119], v[52:53], v[166:167] op_sel_hi:[1,0,1]
	v_pk_fma_f32 v[168:169], v[120:121], v[52:53], v[168:169] op_sel_hi:[1,0,1]
	v_pk_fma_f32 v[170:171], v[122:123], v[52:53], v[170:171] op_sel_hi:[1,0,1]
	v_pk_fma_f32 v[172:173], v[124:125], v[52:53], v[172:173] op_sel_hi:[1,0,1]
	v_pk_fma_f32 v[174:175], v[126:127], v[52:53], v[174:175] op_sel_hi:[1,0,1]
	v_pk_fma_f32 v[176:177], v[128:129], v[52:53], v[176:177] op_sel_hi:[1,0,1]
	s_waitcnt lgkmcnt(4)
; #define LAS __attribute__((address_space(3)))
; DI void phase_ln1(KArgs args, LAS unsigned char* L, const Ctx& c) {
;     ...
;                 for (int e4 = 0; e4 < 4; ++e4) { const f32x4 w4 = *(const LAS f32x4*)(wp + 4 * e4); lg[4 * e4] += xv * w4[0]; lg[4 * e4 + 1] += xv * w4[1]; lg[4 * e4 + 2] += xv * w4[2]; lg[4 * e4 + 3] += xv * w4[3]; } }
;             asm volatile("" ::: "memory"); }
;         const bool h5 = (lane & 32) != 0, h4 = (lane & 16) != 0, h3 = (lane & 8) != 0, h2 = (lane & 4) != 0;
;         const int eid = (h5 ? 8 : 0) + (h4 ? 4 : 0) + (h3 ? 2 : 0) + (h2 ? 1 : 0);
;         float a8[8], b4[4], c2[2], d;
; #pragma unroll
;         for (int k = 0; k < 8; ++k) { const float snd = h5 ? lg[k] : lg[k + 8]; a8[k] = (h5 ? lg[k + 8] : lg[k]) + __shfl_xor(snd, 32); }
; #pragma unroll
;         for (int k = 0; k < 4; ++k) { const float snd = h4 ? a8[k] : a8[k + 4]; b4[k] = (h4 ? a8[k + 4] : a8[k]) + __shfl_xor(snd, 16); }
; #pragma unroll
;         for (int k = 0; k < 2; ++k) { const float snd = h3 ? b4[k] : b4[k + 2]; c2[k] = (h3 ? b4[k + 2] : b4[k]) + __shfl_xor(snd, 8); }
;         { const float snd = h2 ? c2[0] : c2[1]; d = (h2 ? c2[1] : c2[0]) + __shfl_xor(snd, 4); }
;         d += __shfl_xor(d, 2); d += __shfl_xor(d, 1);
;         float mx = d;
;         mx = fmaxf(mx, __shfl_xor(mx, 32)); mx = fmaxf(mx, __shfl_xor(mx, 16)); mx = fmaxf(mx, __shfl_xor(mx, 8)); mx = fmaxf(mx, __shfl_xor(mx, 4));
;         const float pe = expf(d - mx); float den = pe;
;         den += __shfl_xor(den, 32); den += __shfl_xor(den, 16); den += __shfl_xor(den, 8); den += __shfl_xor(den, 4);
;         if ((lane & 3) == 0 && !c.dry) { AFF[(size_t)eid * T_ALL + tok] = pe / den; SLOT[tok * 16 + eid] = -1; }
	ds_read_b128 v[114:117], v72
	ds_read_b128 v[118:121], v73
	ds_read_b128 v[122:125], v74
	ds_read_b128 v[126:129], v75
	v_pk_fma_f32 v[162:163], v[130:131], v[52:53], v[162:163] op_sel:[0,1,0]
	v_pk_fma_f32 v[164:165], v[132:133], v[52:53], v[164:165] op_sel:[0,1,0]
	v_pk_fma_f32 v[166:167], v[134:135], v[52:53], v[166:167] op_sel:[0,1,0]
	v_pk_fma_f32 v[168:169], v[136:137], v[52:53], v[168:169] op_sel:[0,1,0]
	v_pk_fma_f32 v[170:171], v[138:139], v[52:53], v[170:171] op_sel:[0,1,0]
	v_pk_fma_f32 v[172:173], v[140:141], v[52:53], v[172:173] op_sel:[0,1,0]
	v_pk_fma_f32 v[174:175], v[142:143], v[52:53], v[174:175] op_sel:[0,1,0]
	v_pk_fma_f32 v[176:177], v[144:145], v[52:53], v[176:177] op_sel:[0,1,0]
	s_waitcnt lgkmcnt(4)
	v_pk_fma_f32 v[162:163], v[146:147], v[50:51], v[162:163] op_sel_hi:[1,0,1]
	v_pk_fma_f32 v[164:165], v[148:149], v[50:51], v[164:165] op_sel_hi:[1,0,1]
	v_pk_fma_f32 v[166:167], v[150:151], v[50:51], v[166:167] op_sel_hi:[1,0,1]
	v_pk_fma_f32 v[168:169], v[152:153], v[50:51], v[168:169] op_sel_hi:[1,0,1]
	v_pk_fma_f32 v[170:171], v[154:155], v[50:51], v[170:171] op_sel_hi:[1,0,1]
	v_pk_fma_f32 v[172:173], v[156:157], v[50:51], v[172:173] op_sel_hi:[1,0,1]
	v_pk_fma_f32 v[174:175], v[158:159], v[50:51], v[174:175] op_sel_hi:[1,0,1]
	v_pk_fma_f32 v[176:177], v[160:161], v[50:51], v[176:177] op_sel_hi:[1,0,1]
	s_waitcnt lgkmcnt(0)
	v_pk_fma_f32 v[162:163], v[114:115], v[50:51], v[162:163] op_sel:[0,1,0]
	v_pk_fma_f32 v[164:165], v[116:117], v[50:51], v[164:165] op_sel:[0,1,0]
	v_pk_fma_f32 v[166:167], v[118:119], v[50:51], v[166:167] op_sel:[0,1,0]
	v_pk_fma_f32 v[168:169], v[120:121], v[50:51], v[168:169] op_sel:[0,1,0]
	v_pk_fma_f32 v[170:171], v[122:123], v[50:51], v[170:171] op_sel:[0,1,0]
	v_pk_fma_f32 v[172:173], v[124:125], v[50:51], v[172:173] op_sel:[0,1,0]
	v_pk_fma_f32 v[174:175], v[126:127], v[50:51], v[174:175] op_sel:[0,1,0]
	v_pk_fma_f32 v[176:177], v[128:129], v[50:51], v[176:177] op_sel:[0,1,0]
	v_permlane32_swap_b32_e32 v162, v170
	v_permlane32_swap_b32_e32 v163, v171
	v_permlane32_swap_b32_e32 v164, v172
	v_permlane32_swap_b32_e32 v165, v173
	v_permlane32_swap_b32_e32 v166, v174
	v_permlane32_swap_b32_e32 v167, v175
	v_permlane32_swap_b32_e32 v168, v176
	v_permlane32_swap_b32_e32 v169, v177
	v_add_f32_e32 v162, v162, v170
	v_add_f32_e32 v163, v163, v171
	v_add_f32_e32 v164, v164, v172
	v_add_f32_e32 v165, v165, v173
	v_add_f32_e32 v166, v166, v174
	v_add_f32_e32 v167, v167, v175
	v_add_f32_e32 v168, v168, v176
	v_add_f32_e32 v169, v169, v177
	v_permlane16_swap_b32_e32 v162, v166
	v_permlane16_swap_b32_e32 v163, v167
	v_permlane16_swap_b32_e32 v164, v168
	v_permlane16_swap_b32_e32 v165, v169
	v_add_f32_e32 v162, v162, v166
	v_add_f32_e32 v163, v163, v167
	v_add_f32_e32 v164, v164, v168
	v_add_f32_e32 v165, v165, v169
	s_nop 1
	v_add_f32_dpp v178, v162, v162 row_ror:8 row_mask:0xf bank_mask:0x3
	v_add_f32_dpp v179, v163, v163 row_ror:8 row_mask:0xf bank_mask:0x3
	v_add_f32_dpp v178, v164, v164 row_ror:8 row_mask:0xf bank_mask:0xc
	v_add_f32_dpp v179, v165, v165 row_ror:8 row_mask:0xf bank_mask:0xc
	s_nop 1
	v_add_f32_dpp v180, v178, v178 row_shl:4 row_mask:0xf bank_mask:0x5
	v_add_f32_dpp v180, v179, v179 row_shr:4 row_mask:0xf bank_mask:0xa
	s_nop 1
	v_add_f32_dpp v180, v180, v180 quad_perm:[2,3,0,1] row_mask:0xf bank_mask:0xf
	s_nop 1
	v_add_f32_dpp v180, v180, v180 quad_perm:[1,0,3,2] row_mask:0xf bank_mask:0xf
	s_nop 1
	v_max_f32_dpp v181, v180, v180 row_ror:4 row_mask:0xf bank_mask:0xf
	s_nop 1
	v_max_f32_dpp v181, v181, v181 row_ror:8 row_mask:0xf bank_mask:0xf
	s_nop 0
	v_mov_b32_e32 v182, v181
	s_nop 1
	v_permlane16_swap_b32_e32 v181, v182
	v_max_f32_e32 v181, v181, v182
	v_mov_b32_e32 v182, v181
	s_nop 1
	v_permlane32_swap_b32_e32 v181, v182
	v_max_f32_e32 v55, v181, v182
	v_sub_f32_e32 v54, v180, v55
	v_mul_f32_e32 v55, 0x3fb8aa3b, v54
	v_fma_f32 v56, v54, s1, -v55
	v_rndne_f32_e32 v57, v55
	v_fmac_f32_e32 v56, 0x32a5705f, v54
	v_sub_f32_e32 v55, v55, v57
	v_add_f32_e32 v55, v55, v56
	v_exp_f32_e32 v55, v55
	v_cvt_i32_f32_e32 v56, v57
	s_mov_b32 s1, 0xc2ce8ed0
	v_cmp_ngt_f32_e32 vcc, s1, v54
	s_mov_b32 s1, 0x42b17218
	v_ldexp_f32 v55, v55, v56
	v_cndmask_b32_e32 v55, 0, v55, vcc
	v_cmp_nlt_f32_e32 vcc, s1, v54
	s_nop 1
	v_cndmask_b32_e32 v54, v213, v55, vcc
	v_mov_b32_e32 v184, v54
	v_mov_b32_e32 v185, v54
	s_nop 1
	v_permlane32_swap_b32_e32 v184, v185
	v_add_f32_e32 v184, v184, v185
	v_mov_b32_e32 v185, v184
	s_nop 1
	v_permlane16_swap_b32_e32 v184, v185
	v_add_f32_e32 v184, v184, v185
	s_nop 1
	v_add_f32_dpp v184, v184, v184 row_ror:8 row_mask:0xf bank_mask:0xf
	s_nop 1
	v_add_f32_dpp v48, v184, v184 row_ror:4 row_mask:0xf bank_mask:0xf
	s_and_saveexec_b64 s[24:25], s[12:13]
	s_cbranch_execz .LBB0_1219
	v_div_scale_f32 v49, s[28:29], v48, v48, v54
	v_rcp_f32_e32 v50, v49
	v_div_scale_f32 v51, vcc, v54, v48, v54
	v_fma_f32 v52, -v49, v50, 1.0
	v_fmac_f32_e32 v50, v52, v50
	v_mul_f32_e32 v52, v51, v50
	v_fma_f32 v53, -v49, v52, v51
	v_fmac_f32_e32 v52, v53, v50
	v_fma_f32 v49, -v49, v52, v51
	v_div_fmas_f32 v49, v49, v50, v52
	v_div_fixup_f32 v48, v49, v48, v54
	global_store_dword v[36:37], v48, off
	v_mov_b32_e32 v48, -1
	global_store_dword v[38:39], v48, off
	s_branch .LBB0_1219
